# stack: GU 288-row tiles + w_gu conversion moved to attention idle WGs + scalar-loaded attention sinks + 8-byte aligned MFMA runs
# baseline (speedup 1.0000x reference)
; #define PG8_STAGE(bufoff, gbase, voff) do { _Pragma("unroll") for (int _i = 0; _i < 2; ++_i) \
;         __builtin_amdgcn_global_load_lds((const unsigned*)((const char*)(gbase) + (voff)[_i]), (PG8_LAS unsigned*)(lds + (bufoff) + ldsw + _i * 8192), 16, 0, 0); } while (0)
; #define PG8_LDA(dst, b, h) do { _Pragma("unroll") for (int m = 0; m < 4; ++m) _Pragma("unroll") for (int k = 0; k < 2; ++k) dst[m][k] = *(const PG8_LAS bf16x8*)(lds + PG8_SA(b, h) + aoff + m * 2048 + k * 1024); } while (0)
; #define PG8_LDB(dst, b, h) do { _Pragma("unroll") for (int n = 0; n < 2; ++n) _Pragma("unroll") for (int k = 0; k < 2; ++k) dst[n][k] = *(const PG8_LAS bf16x8*)(lds + PG8_SB(b, h) + boff + n * 2048 + k * 1024); } while (0)
; #define PG8_MMA(ai, bj, At, Bt) do { __builtin_amdgcn_s_setprio(1); _Pragma("unroll") for (int m = 0; m < 4; ++m) _Pragma("unroll") for (int n = 0; n < 2; ++n) _Pragma("unroll") for (int k = 0; k < 2; ++k) \
;         acc[ai][bj][m][n] = __builtin_amdgcn_mfma_f32_16x16x32_bf16(Bt[n][k], At[m][k], acc[ai][bj][m][n], 0, 0, 0); __builtin_amdgcn_s_setprio(0); } while (0)
; #define PG8_WAIT_V(n) asm volatile("s_waitcnt vmcnt(" #n ")" ::: "memory")
; #define PG8_WAIT_L(n) asm volatile("s_waitcnt lgkmcnt(" #n ")" ::: "memory")
; template <class Epi, class Sched, bool ALIGN_EPI = false, bool SP2 = false>
; __device__ __forceinline__ void gemm_phase(PG8_LAS unsigned char* lds, const Gemm g, const Sched& S, const Epi& E) {
;     ...
;             const bool last = (t == nt - 2);
;             const char* a1 = cA + (size_t)(t + 1) * kstep;
;             const char* a2 = last ? nA : cA + (size_t)(t + 2) * kstep; const char* b2 = last ? nB : cB + (size_t)(t + 2) * kstep;
;             const char* a3 = a2 + kstep; const char* b3 = b2 + kstep;
;             if (last && has_next) S.a_ready(nxt);
;             if constexpr (SP2) {
;             PG8_LDB(B0, 0, 0); PG8_LDB(B1, 0, 1); PG8_SCHED; PG8_LDA(At, 0, 0); PG8_STAGE(PG8_SA(1, 1), a1 + hstep, voffA);
;             PG8_WAIT_V(8); PG8_WAIT_L(0); PG8_BAR; PG8_MMA(0, 0, At, B0); PG8_MMA(0, 1, At, B1); PG8_BAR; PG8_SCHED;
;             PG8_LDA(At, 0, 1); PG8_STAGE(PG8_SB(0, 0), b2, voffB); PG8_STAGE(PG8_SB(0, 1), b2 + hstep, voffB); PG8_STAGE(PG8_SA(0, 0), a2, voffA);
;             PG8_WAIT_V(8); PG8_WAIT_L(0); PG8_BAR; PG8_MMA(1, 0, At, B0); PG8_MMA(1, 1, At, B1); PG8_BAR; PG8_SCHED;
.LBB0_35:
	s_add_u32 s24, s0, 0xfffc0080
	s_addc_u32 s25, s1, -1
	s_cmp_eq_u32 s51, 12
	s_cselect_b32 s27, s4, s25
	s_cselect_b32 s26, s5, s24
	s_cselect_b32 s25, s3, s50
	s_cselect_b32 s24, s19, s49
	s_add_i32 s52, 0, 0x10000
	s_add_i32 s54, 0, 0x14000
	v_add_u32_e32 v156, s52, v141
	v_add_u32_e32 v172, s54, v141
	ds_read_b128 v[144:147], v156
	ds_read_b128 v[148:151], v156 offset:1024
	ds_read_b128 v[152:155], v156 offset:2048
	ds_read_b128 v[156:159], v156 offset:3072
	ds_read_b128 v[160:163], v172
	ds_read_b128 v[164:167], v172 offset:1024
	ds_read_b128 v[168:171], v172 offset:2048
	ds_read_b128 v[172:175], v172 offset:3072
	s_add_i32 m0, s40, 0xc000
	ds_read_b128 v[176:179], v143
	ds_read_b128 v[180:183], v143 offset:1024
	ds_read_b128 v[194:197], v143 offset:2048
	ds_read_b128 v[198:201], v143 offset:3072
	ds_read_b128 v[202:205], v143 offset:4096
	ds_read_b128 v[206:209], v143 offset:5120
	ds_read_b128 v[210:213], v143 offset:6144
	ds_read_b128 v[228:231], v143 offset:7168
	ds_read_b128 v[232:235], v249
	ds_read_b128 v[136:139], v249 offset:1024
	global_load_lds_dwordx4 v134, s[0:1]
	s_add_i32 m0, s40, 0xe000
	s_nop 0
	global_load_lds_dwordx4 v130, s[0:1]
	s_waitcnt vmcnt(9)
	s_waitcnt lgkmcnt(0)
	s_barrier
	s_setprio 1
	s_waitcnt lgkmcnt(0)
	v_mfma_f32_16x16x32_bf16 v[124:127], v[144:147], v[176:179], v[124:127]
	v_mfma_f32_16x16x32_bf16 v[116:119], v[152:155], v[176:179], v[116:119]
	v_mfma_f32_16x16x32_bf16 v[108:111], v[144:147], v[194:197], v[108:111]
	v_mfma_f32_16x16x32_bf16 v[100:103], v[152:155], v[194:197], v[100:103]
	v_mfma_f32_16x16x32_bf16 v[92:95], v[144:147], v[202:205], v[92:95]
	v_mfma_f32_16x16x32_bf16 v[84:87], v[152:155], v[202:205], v[84:87]
	v_mfma_f32_16x16x32_bf16 v[76:79], v[144:147], v[210:213], v[76:79]
	v_mfma_f32_16x16x32_bf16 v[68:71], v[152:155], v[210:213], v[68:71]
	v_mfma_f32_16x16x32_bf16 v[124:127], v[148:151], v[180:183], v[124:127]
	v_mfma_f32_16x16x32_bf16 v[116:119], v[156:159], v[180:183], v[116:119]
	v_mfma_f32_16x16x32_bf16 v[108:111], v[148:151], v[198:201], v[108:111]
	v_mfma_f32_16x16x32_bf16 v[100:103], v[156:159], v[198:201], v[100:103]
	v_mfma_f32_16x16x32_bf16 v[92:95], v[148:151], v[206:209], v[92:95]
	v_mfma_f32_16x16x32_bf16 v[84:87], v[156:159], v[206:209], v[84:87]
	v_mfma_f32_16x16x32_bf16 v[76:79], v[148:151], v[228:231], v[76:79]
	v_mfma_f32_16x16x32_bf16 v[68:71], v[156:159], v[228:231], v[68:71]
	s_setprio 0
	s_setprio 1
	v_mfma_f32_16x16x32_bf16 v[120:123], v[160:163], v[176:179], v[120:123]
	v_mfma_f32_16x16x32_bf16 v[112:115], v[168:171], v[176:179], v[112:115]
	v_mfma_f32_16x16x32_bf16 v[104:107], v[160:163], v[194:197], v[104:107]
	v_mfma_f32_16x16x32_bf16 v[96:99], v[168:171], v[194:197], v[96:99]
	v_mfma_f32_16x16x32_bf16 v[88:91], v[160:163], v[202:205], v[88:91]
	v_mfma_f32_16x16x32_bf16 v[80:83], v[168:171], v[202:205], v[80:83]
	v_mfma_f32_16x16x32_bf16 v[72:75], v[160:163], v[210:213], v[72:75]
	v_mfma_f32_16x16x32_bf16 v[64:67], v[168:171], v[210:213], v[64:67]
	v_mfma_f32_16x16x32_bf16 v[120:123], v[164:167], v[180:183], v[120:123]
	v_mfma_f32_16x16x32_bf16 v[112:115], v[172:175], v[180:183], v[112:115]
	v_mfma_f32_16x16x32_bf16 v[104:107], v[164:167], v[198:201], v[104:107]
	v_mfma_f32_16x16x32_bf16 v[96:99], v[172:175], v[198:201], v[96:99]
	v_mfma_f32_16x16x32_bf16 v[88:91], v[164:167], v[206:209], v[88:91]
	v_mfma_f32_16x16x32_bf16 v[80:83], v[172:175], v[206:209], v[80:83]
	v_mfma_f32_16x16x32_bf16 v[72:75], v[164:167], v[228:231], v[72:75]
	v_mfma_f32_16x16x32_bf16 v[64:67], v[172:175], v[228:231], v[64:67]
	v_mfma_f32_16x16x32_bf16 v[236:239], v[144:147], v[232:235], v[236:239]
	v_mfma_f32_16x16x32_bf16 v[240:243], v[152:155], v[232:235], v[240:243]
	v_mfma_f32_16x16x32_bf16 v[244:247], v[160:163], v[232:235], v[244:247]
	v_mfma_f32_16x16x32_bf16 v[224:227], v[168:171], v[232:235], v[224:227]
	v_mfma_f32_16x16x32_bf16 v[236:239], v[148:151], v[136:139], v[236:239]
	v_mfma_f32_16x16x32_bf16 v[240:243], v[156:159], v[136:139], v[240:243]
	v_mfma_f32_16x16x32_bf16 v[244:247], v[164:167], v[136:139], v[244:247]
	v_mfma_f32_16x16x32_bf16 v[224:227], v[172:175], v[136:139], v[224:227]
	s_setprio 0
	s_barrier
	s_add_i32 s52, s52, s39
	s_mov_b32 m0, s52
	ds_read_b128 v[176:179], v143 offset:16384
	ds_read_b128 v[180:183], v143 offset:17408
	ds_read_b128 v[194:197], v143 offset:18432
	ds_read_b128 v[198:201], v143 offset:19456
	ds_read_b128 v[202:205], v143 offset:20480
	ds_read_b128 v[206:209], v143 offset:21504
	ds_read_b128 v[210:213], v143 offset:22528
	ds_read_b128 v[228:231], v143 offset:23552
	global_load_lds_dwordx4 v132, s[24:25]
	s_add_i32 m0, s52, 0x2000
	s_add_u32 s98, s24, 0x40000
	s_addc_u32 s99, s25, 0
	s_add_i32 s54, s54, s39
	global_load_lds_dwordx4 v128, s[24:25]
	s_mov_b32 m0, s54
	s_nop 0
	global_load_lds_dwordx4 v132, s[98:99]
	s_add_i32 m0, s54, 0x2000
	s_nop 0
	global_load_lds_dwordx4 v128, s[98:99]
	s_mov_b32 m0, s40
	s_nop 0
	global_load_lds_dwordx4 v134, s[26:27]
	s_mov_b32 m0, s41
	s_nop 0
	global_load_lds_dwordx4 v130, s[26:27]
	s_and_b32 m0, s39, 0xc00
	s_add_i32 m0, m0, 0x20800
	s_nop 0
	global_load_lds_dwordx4 v248, s[26:27]
	s_nop 0
	s_waitcnt vmcnt(9)
	s_waitcnt lgkmcnt(0)
	s_barrier
; #define PG8_STAGE(bufoff, gbase, voff) do { _Pragma("unroll") for (int _i = 0; _i < 2; ++_i) \
;         __builtin_amdgcn_global_load_lds((const unsigned*)((const char*)(gbase) + (voff)[_i]), (PG8_LAS unsigned*)(lds + (bufoff) + ldsw + _i * 8192), 16, 0, 0); } while (0)
; #define PG8_LDA(dst, b, h) do { _Pragma("unroll") for (int m = 0; m < 4; ++m) _Pragma("unroll") for (int k = 0; k < 2; ++k) dst[m][k] = *(const PG8_LAS bf16x8*)(lds + PG8_SA(b, h) + aoff + m * 2048 + k * 1024); } while (0)
; #define PG8_LDB(dst, b, h) do { _Pragma("unroll") for (int n = 0; n < 2; ++n) _Pragma("unroll") for (int k = 0; k < 2; ++k) dst[n][k] = *(const PG8_LAS bf16x8*)(lds + PG8_SB(b, h) + boff + n * 2048 + k * 1024); } while (0)
; #define PG8_MMA(ai, bj, At, Bt) do { __builtin_amdgcn_s_setprio(1); _Pragma("unroll") for (int m = 0; m < 4; ++m) _Pragma("unroll") for (int n = 0; n < 2; ++n) _Pragma("unroll") for (int k = 0; k < 2; ++k) \
;         acc[ai][bj][m][n] = __builtin_amdgcn_mfma_f32_16x16x32_bf16(Bt[n][k], At[m][k], acc[ai][bj][m][n], 0, 0, 0); __builtin_amdgcn_s_setprio(0); } while (0)
; #define PG8_WAIT_V(n) asm volatile("s_waitcnt vmcnt(" #n ")" ::: "memory")
; #define PG8_WAIT_L(n) asm volatile("s_waitcnt lgkmcnt(" #n ")" ::: "memory")
; #define PG8_BAR __builtin_amdgcn_s_barrier()
; #define PG8_SCHED __builtin_amdgcn_sched_barrier(0)
; template <class Epi, class Sched, bool ALIGN_EPI = false, bool SP2 = false>
; __device__ __forceinline__ void gemm_phase(PG8_LAS unsigned char* lds, const Gemm g, const Sched& S, const Epi& E) {
;     ...
;             PG8_WAIT_V(8); PG8_WAIT_L(0); PG8_BAR; PG8_MMA(1, 0, At, B0); PG8_MMA(1, 1, At, B1); PG8_BAR; PG8_SCHED;
;             PG8_LDB(B0, 1, 0); PG8_LDB(B1, 1, 1); PG8_SCHED; PG8_LDA(At, 1, 0); PG8_STAGE(PG8_SA(0, 1), a2 + hstep, voffA);
;             PG8_WAIT_V(8); PG8_WAIT_L(0); PG8_BAR; PG8_MMA(0, 0, At, B0); PG8_MMA(0, 1, At, B1); PG8_BAR; PG8_SCHED;
	s_setprio 1
	s_waitcnt lgkmcnt(0)
	v_mfma_f32_16x16x32_bf16 v[60:63], v[144:147], v[176:179], v[60:63]
	v_mfma_f32_16x16x32_bf16 v[52:55], v[152:155], v[176:179], v[52:55]
	v_mfma_f32_16x16x32_bf16 v[44:47], v[144:147], v[194:197], v[44:47]
	v_mfma_f32_16x16x32_bf16 v[36:39], v[152:155], v[194:197], v[36:39]
	v_mfma_f32_16x16x32_bf16 v[28:31], v[144:147], v[202:205], v[28:31]
	v_mfma_f32_16x16x32_bf16 v[20:23], v[152:155], v[202:205], v[20:23]
	v_mfma_f32_16x16x32_bf16 v[12:15], v[144:147], v[210:213], v[12:15]
	v_mfma_f32_16x16x32_bf16 v[4:7], v[152:155], v[210:213], v[4:7]
	v_mfma_f32_16x16x32_bf16 v[60:63], v[148:151], v[180:183], v[60:63]
	v_mfma_f32_16x16x32_bf16 v[52:55], v[156:159], v[180:183], v[52:55]
	v_mfma_f32_16x16x32_bf16 v[44:47], v[148:151], v[198:201], v[44:47]
	v_mfma_f32_16x16x32_bf16 v[36:39], v[156:159], v[198:201], v[36:39]
	v_mfma_f32_16x16x32_bf16 v[28:31], v[148:151], v[206:209], v[28:31]
	v_mfma_f32_16x16x32_bf16 v[20:23], v[156:159], v[206:209], v[20:23]
	v_mfma_f32_16x16x32_bf16 v[12:15], v[148:151], v[228:231], v[12:15]
	v_mfma_f32_16x16x32_bf16 v[4:7], v[156:159], v[228:231], v[4:7]
	s_setprio 0
	s_setprio 1
	v_mfma_f32_16x16x32_bf16 v[56:59], v[160:163], v[176:179], v[56:59]
	v_mfma_f32_16x16x32_bf16 v[48:51], v[168:171], v[176:179], v[48:51]
	v_mfma_f32_16x16x32_bf16 v[40:43], v[160:163], v[194:197], v[40:43]
	v_mfma_f32_16x16x32_bf16 v[32:35], v[168:171], v[194:197], v[32:35]
	v_mfma_f32_16x16x32_bf16 v[24:27], v[160:163], v[202:205], v[24:27]
	v_mfma_f32_16x16x32_bf16 v[16:19], v[168:171], v[202:205], v[16:19]
	v_mfma_f32_16x16x32_bf16 v[8:11], v[160:163], v[210:213], v[8:11]
	v_mfma_f32_16x16x32_bf16 v[0:3], v[168:171], v[210:213], v[0:3]
	v_mfma_f32_16x16x32_bf16 v[56:59], v[164:167], v[180:183], v[56:59]
	v_mfma_f32_16x16x32_bf16 v[48:51], v[172:175], v[180:183], v[48:51]
	v_mfma_f32_16x16x32_bf16 v[40:43], v[164:167], v[198:201], v[40:43]
	v_mfma_f32_16x16x32_bf16 v[32:35], v[172:175], v[198:201], v[32:35]
	v_mfma_f32_16x16x32_bf16 v[24:27], v[164:167], v[206:209], v[24:27]
	v_mfma_f32_16x16x32_bf16 v[16:19], v[172:175], v[206:209], v[16:19]
	v_mfma_f32_16x16x32_bf16 v[8:11], v[164:167], v[228:231], v[8:11]
	v_mfma_f32_16x16x32_bf16 v[0:3], v[172:175], v[228:231], v[0:3]
	s_setprio 0
	s_barrier
	s_add_i32 s52, 0, 0x18000
	s_add_i32 s53, 0, 0x1c000
	v_add_u32_e32 v156, s52, v141
	v_add_u32_e32 v172, s53, v141
	ds_read_b128 v[144:147], v156
	ds_read_b128 v[148:151], v156 offset:1024
	ds_read_b128 v[152:155], v156 offset:2048
	ds_read_b128 v[156:159], v156 offset:3072
	ds_read_b128 v[160:163], v172
	ds_read_b128 v[164:167], v172 offset:1024
	ds_read_b128 v[168:171], v172 offset:2048
	ds_read_b128 v[172:175], v172 offset:3072
	s_add_u32 s26, s26, 0x40000
	s_addc_u32 s27, s27, 0
	s_mov_b32 m0, s42
	ds_read_b128 v[176:179], v143 offset:32768
	ds_read_b128 v[180:183], v143 offset:33792
	ds_read_b128 v[194:197], v143 offset:34816
	ds_read_b128 v[198:201], v143 offset:35840
	ds_read_b128 v[202:205], v143 offset:36864
	ds_read_b128 v[206:209], v143 offset:37888
	ds_read_b128 v[210:213], v143 offset:38912
	ds_read_b128 v[228:231], v143 offset:39936
	ds_read_b128 v[232:235], v249 offset:4096
	ds_read_b128 v[136:139], v249 offset:5120
	global_load_lds_dwordx4 v134, s[26:27]
	s_mov_b32 m0, s43
	s_nop 0
	global_load_lds_dwordx4 v130, s[26:27]
	s_nop 0
	s_waitcnt vmcnt(9)
	s_waitcnt lgkmcnt(0)
	s_barrier
	s_setprio 1
	s_waitcnt lgkmcnt(0)
	v_mfma_f32_16x16x32_bf16 v[124:127], v[144:147], v[176:179], v[124:127]
	v_mfma_f32_16x16x32_bf16 v[116:119], v[152:155], v[176:179], v[116:119]
	v_mfma_f32_16x16x32_bf16 v[108:111], v[144:147], v[194:197], v[108:111]
	v_mfma_f32_16x16x32_bf16 v[100:103], v[152:155], v[194:197], v[100:103]
	v_mfma_f32_16x16x32_bf16 v[92:95], v[144:147], v[202:205], v[92:95]
	v_mfma_f32_16x16x32_bf16 v[84:87], v[152:155], v[202:205], v[84:87]
	v_mfma_f32_16x16x32_bf16 v[76:79], v[144:147], v[210:213], v[76:79]
	v_mfma_f32_16x16x32_bf16 v[68:71], v[152:155], v[210:213], v[68:71]
	v_mfma_f32_16x16x32_bf16 v[124:127], v[148:151], v[180:183], v[124:127]
	v_mfma_f32_16x16x32_bf16 v[116:119], v[156:159], v[180:183], v[116:119]
	v_mfma_f32_16x16x32_bf16 v[108:111], v[148:151], v[198:201], v[108:111]
	v_mfma_f32_16x16x32_bf16 v[100:103], v[156:159], v[198:201], v[100:103]
	v_mfma_f32_16x16x32_bf16 v[92:95], v[148:151], v[206:209], v[92:95]
	v_mfma_f32_16x16x32_bf16 v[84:87], v[156:159], v[206:209], v[84:87]
	v_mfma_f32_16x16x32_bf16 v[76:79], v[148:151], v[228:231], v[76:79]
	v_mfma_f32_16x16x32_bf16 v[68:71], v[156:159], v[228:231], v[68:71]
	s_setprio 0
	s_setprio 1
	v_mfma_f32_16x16x32_bf16 v[120:123], v[160:163], v[176:179], v[120:123]
	v_mfma_f32_16x16x32_bf16 v[112:115], v[168:171], v[176:179], v[112:115]
	v_mfma_f32_16x16x32_bf16 v[104:107], v[160:163], v[194:197], v[104:107]
	v_mfma_f32_16x16x32_bf16 v[96:99], v[168:171], v[194:197], v[96:99]
	v_mfma_f32_16x16x32_bf16 v[88:91], v[160:163], v[202:205], v[88:91]
	v_mfma_f32_16x16x32_bf16 v[80:83], v[168:171], v[202:205], v[80:83]
	v_mfma_f32_16x16x32_bf16 v[72:75], v[160:163], v[210:213], v[72:75]
	v_mfma_f32_16x16x32_bf16 v[64:67], v[168:171], v[210:213], v[64:67]
	v_mfma_f32_16x16x32_bf16 v[120:123], v[164:167], v[180:183], v[120:123]
	v_mfma_f32_16x16x32_bf16 v[112:115], v[172:175], v[180:183], v[112:115]
	v_mfma_f32_16x16x32_bf16 v[104:107], v[164:167], v[198:201], v[104:107]
	v_mfma_f32_16x16x32_bf16 v[96:99], v[172:175], v[198:201], v[96:99]
	v_mfma_f32_16x16x32_bf16 v[88:91], v[164:167], v[206:209], v[88:91]
	v_mfma_f32_16x16x32_bf16 v[80:83], v[172:175], v[206:209], v[80:83]
	v_mfma_f32_16x16x32_bf16 v[72:75], v[164:167], v[228:231], v[72:75]
	v_mfma_f32_16x16x32_bf16 v[64:67], v[172:175], v[228:231], v[64:67]
	v_mfma_f32_16x16x32_bf16 v[236:239], v[144:147], v[232:235], v[236:239]
	v_mfma_f32_16x16x32_bf16 v[240:243], v[152:155], v[232:235], v[240:243]
	v_mfma_f32_16x16x32_bf16 v[244:247], v[160:163], v[232:235], v[244:247]
	v_mfma_f32_16x16x32_bf16 v[224:227], v[168:171], v[232:235], v[224:227]
	v_mfma_f32_16x16x32_bf16 v[236:239], v[148:151], v[136:139], v[236:239]
	v_mfma_f32_16x16x32_bf16 v[240:243], v[156:159], v[136:139], v[240:243]
	v_mfma_f32_16x16x32_bf16 v[244:247], v[164:167], v[136:139], v[244:247]
	v_mfma_f32_16x16x32_bf16 v[224:227], v[172:175], v[136:139], v[224:227]
	s_setprio 0
	s_barrier
; #define PG8_STAGE(bufoff, gbase, voff) do { _Pragma("unroll") for (int _i = 0; _i < 2; ++_i) \
;         __builtin_amdgcn_global_load_lds((const unsigned*)((const char*)(gbase) + (voff)[_i]), (PG8_LAS unsigned*)(lds + (bufoff) + ldsw + _i * 8192), 16, 0, 0); } while (0)
; #define PG8_LDA(dst, b, h) do { _Pragma("unroll") for (int m = 0; m < 4; ++m) _Pragma("unroll") for (int k = 0; k < 2; ++k) dst[m][k] = *(const PG8_LAS bf16x8*)(lds + PG8_SA(b, h) + aoff + m * 2048 + k * 1024); } while (0)
; #define PG8_MMA(ai, bj, At, Bt) do { __builtin_amdgcn_s_setprio(1); _Pragma("unroll") for (int m = 0; m < 4; ++m) _Pragma("unroll") for (int n = 0; n < 2; ++n) _Pragma("unroll") for (int k = 0; k < 2; ++k) \
;         acc[ai][bj][m][n] = __builtin_amdgcn_mfma_f32_16x16x32_bf16(Bt[n][k], At[m][k], acc[ai][bj][m][n], 0, 0, 0); __builtin_amdgcn_s_setprio(0); } while (0)
; #define PG8_WAIT_V(n) asm volatile("s_waitcnt vmcnt(" #n ")" ::: "memory")
; #define PG8_WAIT_L(n) asm volatile("s_waitcnt lgkmcnt(" #n ")" ::: "memory")
; #define PG8_BAR __builtin_amdgcn_s_barrier()
; #define PG8_SCHED __builtin_amdgcn_sched_barrier(0)
; template <class Epi, class Sched, bool ALIGN_EPI = false, bool SP2 = false>
; __device__ __forceinline__ void gemm_phase(PG8_LAS unsigned char* lds, const Gemm g, const Sched& S, const Epi& E) {
;     ...
;             PG8_WAIT_V(8); PG8_WAIT_L(0); PG8_BAR; PG8_MMA(0, 0, At, B0); PG8_MMA(0, 1, At, B1); PG8_BAR; PG8_SCHED;
;             PG8_LDA(At, 1, 1); PG8_STAGE(PG8_SB(1, 0), b3, voffB); PG8_STAGE(PG8_SB(1, 1), b3 + hstep, voffB); PG8_STAGE(PG8_SA(1, 0), a3, voffA);
;             PG8_WAIT_V(8); PG8_WAIT_L(0); PG8_BAR; PG8_MMA(1, 0, At, B0); PG8_MMA(1, 1, At, B1); PG8_BAR; PG8_SCHED;
	s_add_i32 s52, s52, s39
	s_add_u32 s98, s24, 0x80
	s_addc_u32 s99, s25, 0
	s_mov_b32 m0, s52
	ds_read_b128 v[176:179], v143 offset:49152
	ds_read_b128 v[180:183], v143 offset:50176
	ds_read_b128 v[194:197], v143 offset:51200
	ds_read_b128 v[198:201], v143 offset:52224
	ds_read_b128 v[202:205], v143 offset:53248
	ds_read_b128 v[206:209], v143 offset:54272
	ds_read_b128 v[210:213], v143 offset:55296
	ds_read_b128 v[228:231], v143 offset:56320
	global_load_lds_dwordx4 v132, s[98:99]
	s_add_i32 m0, s52, 0x2000
	s_add_u32 s100, s26, 0xfffc0080
	s_addc_u32 s101, s27, -1
	s_add_i32 s53, s53, s39
	global_load_lds_dwordx4 v128, s[98:99]
	s_add_u32 s98, s98, 0x40000
	s_addc_u32 s99, s99, 0
	s_mov_b32 m0, s53
	s_nop 0
	global_load_lds_dwordx4 v132, s[98:99]
	s_add_i32 m0, s53, 0x2000
	s_nop 0
	global_load_lds_dwordx4 v128, s[98:99]
	s_mov_b32 m0, s44
	s_nop 0
	global_load_lds_dwordx4 v134, s[100:101]
	s_mov_b32 m0, s45
	s_nop 0
	global_load_lds_dwordx4 v130, s[100:101]
	s_and_b32 m0, s39, 0xc00
	s_add_i32 m0, m0, 0x21800
	s_nop 0
	global_load_lds_dwordx4 v248, s[100:101]
	s_nop 0
	s_waitcnt vmcnt(9)
	s_waitcnt lgkmcnt(0)
	s_barrier
	s_setprio 1
	s_waitcnt lgkmcnt(0)
	v_mfma_f32_16x16x32_bf16 v[60:63], v[144:147], v[176:179], v[60:63]
	v_mfma_f32_16x16x32_bf16 v[52:55], v[152:155], v[176:179], v[52:55]
	v_mfma_f32_16x16x32_bf16 v[44:47], v[144:147], v[194:197], v[44:47]
	v_mfma_f32_16x16x32_bf16 v[36:39], v[152:155], v[194:197], v[36:39]
	v_mfma_f32_16x16x32_bf16 v[28:31], v[144:147], v[202:205], v[28:31]
	v_mfma_f32_16x16x32_bf16 v[20:23], v[152:155], v[202:205], v[20:23]
	v_mfma_f32_16x16x32_bf16 v[12:15], v[144:147], v[210:213], v[12:15]
	v_mfma_f32_16x16x32_bf16 v[4:7], v[152:155], v[210:213], v[4:7]
	v_mfma_f32_16x16x32_bf16 v[60:63], v[148:151], v[180:183], v[60:63]
	v_mfma_f32_16x16x32_bf16 v[52:55], v[156:159], v[180:183], v[52:55]
	v_mfma_f32_16x16x32_bf16 v[44:47], v[148:151], v[198:201], v[44:47]
	v_mfma_f32_16x16x32_bf16 v[36:39], v[156:159], v[198:201], v[36:39]
	v_mfma_f32_16x16x32_bf16 v[28:31], v[148:151], v[206:209], v[28:31]
	v_mfma_f32_16x16x32_bf16 v[20:23], v[156:159], v[206:209], v[20:23]
	v_mfma_f32_16x16x32_bf16 v[12:15], v[148:151], v[228:231], v[12:15]
	v_mfma_f32_16x16x32_bf16 v[4:7], v[156:159], v[228:231], v[4:7]
	s_setprio 0
	s_setprio 1
	v_mfma_f32_16x16x32_bf16 v[56:59], v[160:163], v[176:179], v[56:59]
	v_mfma_f32_16x16x32_bf16 v[48:51], v[168:171], v[176:179], v[48:51]
	v_mfma_f32_16x16x32_bf16 v[40:43], v[160:163], v[194:197], v[40:43]
	v_mfma_f32_16x16x32_bf16 v[32:35], v[168:171], v[194:197], v[32:35]
	v_mfma_f32_16x16x32_bf16 v[24:27], v[160:163], v[202:205], v[24:27]
	v_mfma_f32_16x16x32_bf16 v[16:19], v[168:171], v[202:205], v[16:19]
	v_mfma_f32_16x16x32_bf16 v[8:11], v[160:163], v[210:213], v[8:11]
	v_mfma_f32_16x16x32_bf16 v[0:3], v[168:171], v[210:213], v[0:3]
	v_mfma_f32_16x16x32_bf16 v[56:59], v[164:167], v[180:183], v[56:59]
	v_mfma_f32_16x16x32_bf16 v[48:51], v[172:175], v[180:183], v[48:51]
	v_mfma_f32_16x16x32_bf16 v[40:43], v[164:167], v[198:201], v[40:43]
	v_mfma_f32_16x16x32_bf16 v[32:35], v[172:175], v[198:201], v[32:35]
	v_mfma_f32_16x16x32_bf16 v[24:27], v[164:167], v[206:209], v[24:27]
	v_mfma_f32_16x16x32_bf16 v[16:19], v[172:175], v[206:209], v[16:19]
	v_mfma_f32_16x16x32_bf16 v[8:11], v[164:167], v[228:231], v[8:11]
	v_mfma_f32_16x16x32_bf16 v[0:3], v[172:175], v[228:231], v[0:3]
	s_setprio 0
	s_barrier
	s_add_i32 s51, s51, 2
	s_add_u32 s0, s0, 0x100
	s_addc_u32 s1, s1, 0
	s_add_u32 s49, s49, 0x100
	s_addc_u32 s50, s50, 0
	s_cmp_gt_u32 s51, 13
	s_cbranch_scc0 .LBB0_35
	s_and_b64 vcc, exec, s[12:13]
	s_cbranch_vccz .LBB0_38
	s_barrier

; #define PG8_STAGE(bufoff, gbase, voff) do { _Pragma("unroll") for (int _i = 0; _i < 2; ++_i) \
;         __builtin_amdgcn_global_load_lds((const unsigned*)((const char*)(gbase) + (voff)[_i]), (PG8_LAS unsigned*)(lds + (bufoff) + ldsw + _i * 8192), 16, 0, 0); } while (0)
; #define PG8_LDA(dst, b, h) do { _Pragma("unroll") for (int m = 0; m < 4; ++m) _Pragma("unroll") for (int k = 0; k < 2; ++k) dst[m][k] = *(const PG8_LAS bf16x8*)(lds + PG8_SA(b, h) + aoff + m * 2048 + k * 1024); } while (0)
; #define PG8_LDB(dst, b, h) do { _Pragma("unroll") for (int n = 0; n < 2; ++n) _Pragma("unroll") for (int k = 0; k < 2; ++k) dst[n][k] = *(const PG8_LAS bf16x8*)(lds + PG8_SB(b, h) + boff + n * 2048 + k * 1024); } while (0)
; #define PG8_MMA(ai, bj, At, Bt) do { __builtin_amdgcn_s_setprio(1); _Pragma("unroll") for (int m = 0; m < 4; ++m) _Pragma("unroll") for (int n = 0; n < 2; ++n) _Pragma("unroll") for (int k = 0; k < 2; ++k) \
;         acc[ai][bj][m][n] = __builtin_amdgcn_mfma_f32_16x16x32_bf16(Bt[n][k], At[m][k], acc[ai][bj][m][n], 0, 0, 0); __builtin_amdgcn_s_setprio(0); } while (0)
; #define PG8_WAIT_V(n) asm volatile("s_waitcnt vmcnt(" #n ")" ::: "memory")
; #define PG8_WAIT_L(n) asm volatile("s_waitcnt lgkmcnt(" #n ")" ::: "memory")
; template <class Epi, class Sched, bool ALIGN_EPI = false, bool SP2 = false>
; __device__ __forceinline__ void gemm_phase(PG8_LAS unsigned char* lds, const Gemm g, const Sched& S, const Epi& E) {
;     ...
;             const bool last = (t == nt - 2);
;             const char* a1 = cA + (size_t)(t + 1) * kstep;
;             const char* a2 = last ? nA : cA + (size_t)(t + 2) * kstep; const char* b2 = last ? nB : cB + (size_t)(t + 2) * kstep;
;             const char* a3 = a2 + kstep; const char* b3 = b2 + kstep;
;             if (last && has_next) S.a_ready(nxt);
;             if constexpr (SP2) {
;             PG8_LDB(B0, 0, 0); PG8_LDB(B1, 0, 1); PG8_SCHED; PG8_LDA(At, 0, 0); PG8_STAGE(PG8_SA(1, 1), a1 + hstep, voffA);
;             PG8_WAIT_V(8); PG8_WAIT_L(0); PG8_BAR; PG8_MMA(0, 0, At, B0); PG8_MMA(0, 1, At, B1); PG8_BAR; PG8_SCHED;
;             PG8_LDA(At, 0, 1); PG8_STAGE(PG8_SB(0, 0), b2, voffB); PG8_STAGE(PG8_SB(0, 1), b2 + hstep, voffB); PG8_STAGE(PG8_SA(0, 0), a2, voffA);
;             PG8_WAIT_V(8); PG8_WAIT_L(0); PG8_BAR; PG8_MMA(1, 0, At, B0); PG8_MMA(1, 1, At, B1); PG8_BAR; PG8_SCHED;
.LBB0_218:
	s_add_u32 s25, s0, 0xfffc0080
	s_addc_u32 s40, s1, -1
	s_cmp_eq_u32 s93, 12
	s_cselect_b32 s43, s4, s40
	s_cselect_b32 s42, s5, s25
	s_cselect_b32 s41, s27, s92
	s_cselect_b32 s40, s58, s59
	s_add_i32 s94, 0, 0x10000
	s_add_i32 s25, 0, 0x14000
	v_add_u32_e32 v140, s94, v228
	v_add_u32_e32 v156, s25, v228
	ds_read_b128 v[128:131], v140
	ds_read_b128 v[132:135], v140 offset:1024
	ds_read_b128 v[136:139], v140 offset:2048
	ds_read_b128 v[140:143], v140 offset:3072
	ds_read_b128 v[144:147], v156
	ds_read_b128 v[148:151], v156 offset:1024
	ds_read_b128 v[152:155], v156 offset:2048
	ds_read_b128 v[156:159], v156 offset:3072
	s_add_i32 m0, s45, 0xc000
	ds_read_b128 v[160:163], v230
	ds_read_b128 v[164:167], v230 offset:1024
	ds_read_b128 v[168:171], v230 offset:2048
	ds_read_b128 v[172:175], v230 offset:3072
	ds_read_b128 v[176:179], v230 offset:4096
	ds_read_b128 v[180:183], v230 offset:5120
	ds_read_b128 v[204:207], v230 offset:6144
	ds_read_b128 v[208:211], v230 offset:7168
	ds_read_b128 v[212:215], v249
	ds_read_b128 v[232:235], v249 offset:1024
	global_load_lds_dwordx4 v198, s[0:1]
	s_add_i32 m0, s45, 0xe000
	s_nop 0
	global_load_lds_dwordx4 v196, s[0:1]
	s_nop 0
	s_waitcnt vmcnt(9)
	s_waitcnt lgkmcnt(0)
	s_barrier
	s_setprio 1
	s_waitcnt lgkmcnt(0)
	v_mfma_f32_16x16x32_bf16 v[124:127], v[128:131], v[160:163], v[124:127]
	v_mfma_f32_16x16x32_bf16 v[120:123], v[136:139], v[160:163], v[120:123]
	v_mfma_f32_16x16x32_bf16 v[108:111], v[128:131], v[168:171], v[108:111]
	v_mfma_f32_16x16x32_bf16 v[104:107], v[136:139], v[168:171], v[104:107]
	v_mfma_f32_16x16x32_bf16 v[92:95], v[128:131], v[176:179], v[92:95]
	v_mfma_f32_16x16x32_bf16 v[88:91], v[136:139], v[176:179], v[88:91]
	v_mfma_f32_16x16x32_bf16 v[76:79], v[128:131], v[204:207], v[76:79]
	v_mfma_f32_16x16x32_bf16 v[72:75], v[136:139], v[204:207], v[72:75]
	v_mfma_f32_16x16x32_bf16 v[124:127], v[132:135], v[164:167], v[124:127]
	v_mfma_f32_16x16x32_bf16 v[120:123], v[140:143], v[164:167], v[120:123]
	v_mfma_f32_16x16x32_bf16 v[108:111], v[132:135], v[172:175], v[108:111]
	v_mfma_f32_16x16x32_bf16 v[104:107], v[140:143], v[172:175], v[104:107]
	v_mfma_f32_16x16x32_bf16 v[92:95], v[132:135], v[180:183], v[92:95]
	v_mfma_f32_16x16x32_bf16 v[88:91], v[140:143], v[180:183], v[88:91]
	v_mfma_f32_16x16x32_bf16 v[76:79], v[132:135], v[208:211], v[76:79]
	v_mfma_f32_16x16x32_bf16 v[72:75], v[140:143], v[208:211], v[72:75]
	s_setprio 0
	s_setprio 1
	v_mfma_f32_16x16x32_bf16 v[116:119], v[144:147], v[160:163], v[116:119]
	v_mfma_f32_16x16x32_bf16 v[112:115], v[152:155], v[160:163], v[112:115]
	v_mfma_f32_16x16x32_bf16 v[100:103], v[144:147], v[168:171], v[100:103]
	v_mfma_f32_16x16x32_bf16 v[96:99], v[152:155], v[168:171], v[96:99]
	v_mfma_f32_16x16x32_bf16 v[84:87], v[144:147], v[176:179], v[84:87]
	v_mfma_f32_16x16x32_bf16 v[80:83], v[152:155], v[176:179], v[80:83]
	v_mfma_f32_16x16x32_bf16 v[68:71], v[144:147], v[204:207], v[68:71]
	v_mfma_f32_16x16x32_bf16 v[64:67], v[152:155], v[204:207], v[64:67]
	v_mfma_f32_16x16x32_bf16 v[116:119], v[148:151], v[164:167], v[116:119]
	v_mfma_f32_16x16x32_bf16 v[112:115], v[156:159], v[164:167], v[112:115]
	v_mfma_f32_16x16x32_bf16 v[100:103], v[148:151], v[172:175], v[100:103]
	v_mfma_f32_16x16x32_bf16 v[96:99], v[156:159], v[172:175], v[96:99]
	v_mfma_f32_16x16x32_bf16 v[84:87], v[148:151], v[180:183], v[84:87]
	v_mfma_f32_16x16x32_bf16 v[80:83], v[156:159], v[180:183], v[80:83]
	v_mfma_f32_16x16x32_bf16 v[68:71], v[148:151], v[208:211], v[68:71]
	v_mfma_f32_16x16x32_bf16 v[64:67], v[156:159], v[208:211], v[64:67]
	v_mfma_f32_16x16x32_bf16 v[236:239], v[128:131], v[212:215], v[236:239]
	v_mfma_f32_16x16x32_bf16 v[240:243], v[136:139], v[212:215], v[240:243]
	v_mfma_f32_16x16x32_bf16 v[244:247], v[144:147], v[212:215], v[244:247]
	v_mfma_f32_16x16x32_bf16 v[200:203], v[152:155], v[212:215], v[200:203]
	v_mfma_f32_16x16x32_bf16 v[236:239], v[132:135], v[232:235], v[236:239]
	v_mfma_f32_16x16x32_bf16 v[240:243], v[140:143], v[232:235], v[240:243]
	v_mfma_f32_16x16x32_bf16 v[244:247], v[148:151], v[232:235], v[244:247]
	v_mfma_f32_16x16x32_bf16 v[200:203], v[156:159], v[232:235], v[200:203]
	s_setprio 0
	s_barrier
	s_add_i32 s94, s94, s44
	s_mov_b32 m0, s94
	ds_read_b128 v[160:163], v230 offset:16384
	ds_read_b128 v[164:167], v230 offset:17408
	ds_read_b128 v[168:171], v230 offset:18432
	ds_read_b128 v[172:175], v230 offset:19456
	ds_read_b128 v[176:179], v230 offset:20480
	ds_read_b128 v[180:183], v230 offset:21504
	ds_read_b128 v[204:207], v230 offset:22528
	ds_read_b128 v[208:211], v230 offset:23552
	global_load_lds_dwordx4 v184, s[40:41]
	s_add_i32 m0, s94, 0x2000
	s_add_u32 s98, s40, 0x40000
	s_addc_u32 s99, s41, 0
	s_add_i32 s25, s25, s44
	global_load_lds_dwordx4 v194, s[40:41]
	s_mov_b32 m0, s25
	s_nop 0
	global_load_lds_dwordx4 v184, s[98:99]
	s_add_i32 m0, s25, 0x2000
	s_nop 0
	global_load_lds_dwordx4 v194, s[98:99]
	s_mov_b32 m0, s45
	s_nop 0
	global_load_lds_dwordx4 v198, s[42:43]
	s_mov_b32 m0, s46
	s_nop 0
	global_load_lds_dwordx4 v196, s[42:43]
	s_and_b32 m0, s44, 0xc00
	s_add_i32 m0, m0, 0x20800
	s_nop 0
	global_load_lds_dwordx4 v248, s[42:43]
	s_nop 0
	s_waitcnt vmcnt(9)
	s_waitcnt lgkmcnt(0)
	s_barrier
; #define PG8_STAGE(bufoff, gbase, voff) do { _Pragma("unroll") for (int _i = 0; _i < 2; ++_i) \
;         __builtin_amdgcn_global_load_lds((const unsigned*)((const char*)(gbase) + (voff)[_i]), (PG8_LAS unsigned*)(lds + (bufoff) + ldsw + _i * 8192), 16, 0, 0); } while (0)
; #define PG8_LDA(dst, b, h) do { _Pragma("unroll") for (int m = 0; m < 4; ++m) _Pragma("unroll") for (int k = 0; k < 2; ++k) dst[m][k] = *(const PG8_LAS bf16x8*)(lds + PG8_SA(b, h) + aoff + m * 2048 + k * 1024); } while (0)
; #define PG8_LDB(dst, b, h) do { _Pragma("unroll") for (int n = 0; n < 2; ++n) _Pragma("unroll") for (int k = 0; k < 2; ++k) dst[n][k] = *(const PG8_LAS bf16x8*)(lds + PG8_SB(b, h) + boff + n * 2048 + k * 1024); } while (0)
; #define PG8_MMA(ai, bj, At, Bt) do { __builtin_amdgcn_s_setprio(1); _Pragma("unroll") for (int m = 0; m < 4; ++m) _Pragma("unroll") for (int n = 0; n < 2; ++n) _Pragma("unroll") for (int k = 0; k < 2; ++k) \
;         acc[ai][bj][m][n] = __builtin_amdgcn_mfma_f32_16x16x32_bf16(Bt[n][k], At[m][k], acc[ai][bj][m][n], 0, 0, 0); __builtin_amdgcn_s_setprio(0); } while (0)
; #define PG8_WAIT_V(n) asm volatile("s_waitcnt vmcnt(" #n ")" ::: "memory")
; #define PG8_WAIT_L(n) asm volatile("s_waitcnt lgkmcnt(" #n ")" ::: "memory")
; #define PG8_BAR __builtin_amdgcn_s_barrier()
; #define PG8_SCHED __builtin_amdgcn_sched_barrier(0)
; template <class Epi, class Sched, bool ALIGN_EPI = false, bool SP2 = false>
; __device__ __forceinline__ void gemm_phase(PG8_LAS unsigned char* lds, const Gemm g, const Sched& S, const Epi& E) {
;     ...
;             PG8_WAIT_V(8); PG8_WAIT_L(0); PG8_BAR; PG8_MMA(1, 0, At, B0); PG8_MMA(1, 1, At, B1); PG8_BAR; PG8_SCHED;
;             PG8_LDB(B0, 1, 0); PG8_LDB(B1, 1, 1); PG8_SCHED; PG8_LDA(At, 1, 0); PG8_STAGE(PG8_SA(0, 1), a2 + hstep, voffA);
;             PG8_WAIT_V(8); PG8_WAIT_L(0); PG8_BAR; PG8_MMA(0, 0, At, B0); PG8_MMA(0, 1, At, B1); PG8_BAR; PG8_SCHED;
	s_setprio 1
	s_waitcnt lgkmcnt(0)
	v_mfma_f32_16x16x32_bf16 v[60:63], v[128:131], v[160:163], v[60:63]
	v_mfma_f32_16x16x32_bf16 v[56:59], v[136:139], v[160:163], v[56:59]
	v_mfma_f32_16x16x32_bf16 v[44:47], v[128:131], v[168:171], v[44:47]
	v_mfma_f32_16x16x32_bf16 v[40:43], v[136:139], v[168:171], v[40:43]
	v_mfma_f32_16x16x32_bf16 v[28:31], v[128:131], v[176:179], v[28:31]
	v_mfma_f32_16x16x32_bf16 v[24:27], v[136:139], v[176:179], v[24:27]
	v_mfma_f32_16x16x32_bf16 v[12:15], v[128:131], v[204:207], v[12:15]
	v_mfma_f32_16x16x32_bf16 v[8:11], v[136:139], v[204:207], v[8:11]
	v_mfma_f32_16x16x32_bf16 v[60:63], v[132:135], v[164:167], v[60:63]
	v_mfma_f32_16x16x32_bf16 v[56:59], v[140:143], v[164:167], v[56:59]
	v_mfma_f32_16x16x32_bf16 v[44:47], v[132:135], v[172:175], v[44:47]
	v_mfma_f32_16x16x32_bf16 v[40:43], v[140:143], v[172:175], v[40:43]
	v_mfma_f32_16x16x32_bf16 v[28:31], v[132:135], v[180:183], v[28:31]
	v_mfma_f32_16x16x32_bf16 v[24:27], v[140:143], v[180:183], v[24:27]
	v_mfma_f32_16x16x32_bf16 v[12:15], v[132:135], v[208:211], v[12:15]
	v_mfma_f32_16x16x32_bf16 v[8:11], v[140:143], v[208:211], v[8:11]
	s_setprio 0
	s_setprio 1
	v_mfma_f32_16x16x32_bf16 v[52:55], v[144:147], v[160:163], v[52:55]
	v_mfma_f32_16x16x32_bf16 v[48:51], v[152:155], v[160:163], v[48:51]
	v_mfma_f32_16x16x32_bf16 v[36:39], v[144:147], v[168:171], v[36:39]
	v_mfma_f32_16x16x32_bf16 v[32:35], v[152:155], v[168:171], v[32:35]
	v_mfma_f32_16x16x32_bf16 v[20:23], v[144:147], v[176:179], v[20:23]
	v_mfma_f32_16x16x32_bf16 v[16:19], v[152:155], v[176:179], v[16:19]
	v_mfma_f32_16x16x32_bf16 v[4:7], v[144:147], v[204:207], v[4:7]
	v_mfma_f32_16x16x32_bf16 v[0:3], v[152:155], v[204:207], v[0:3]
	v_mfma_f32_16x16x32_bf16 v[52:55], v[148:151], v[164:167], v[52:55]
	v_mfma_f32_16x16x32_bf16 v[48:51], v[156:159], v[164:167], v[48:51]
	v_mfma_f32_16x16x32_bf16 v[36:39], v[148:151], v[172:175], v[36:39]
	v_mfma_f32_16x16x32_bf16 v[32:35], v[156:159], v[172:175], v[32:35]
	v_mfma_f32_16x16x32_bf16 v[20:23], v[148:151], v[180:183], v[20:23]
	v_mfma_f32_16x16x32_bf16 v[16:19], v[156:159], v[180:183], v[16:19]
	v_mfma_f32_16x16x32_bf16 v[4:7], v[148:151], v[208:211], v[4:7]
	v_mfma_f32_16x16x32_bf16 v[0:3], v[156:159], v[208:211], v[0:3]
	s_setprio 0
	s_barrier
	s_add_i32 s25, 0, 0x18000
	s_add_i32 s94, 0, 0x1c000
	v_add_u32_e32 v140, s25, v228
	v_add_u32_e32 v156, s94, v228
	ds_read_b128 v[128:131], v140
	ds_read_b128 v[132:135], v140 offset:1024
	ds_read_b128 v[136:139], v140 offset:2048
	ds_read_b128 v[140:143], v140 offset:3072
	ds_read_b128 v[144:147], v156
	ds_read_b128 v[148:151], v156 offset:1024
	ds_read_b128 v[152:155], v156 offset:2048
	ds_read_b128 v[156:159], v156 offset:3072
	s_add_u32 s98, s42, 0x40000
	s_addc_u32 s99, s43, 0
	s_mov_b32 m0, s47
	ds_read_b128 v[160:163], v230 offset:32768
	ds_read_b128 v[164:167], v230 offset:33792
	ds_read_b128 v[168:171], v230 offset:34816
	ds_read_b128 v[172:175], v230 offset:35840
	ds_read_b128 v[176:179], v230 offset:36864
	ds_read_b128 v[180:183], v230 offset:37888
	ds_read_b128 v[204:207], v230 offset:38912
	ds_read_b128 v[208:211], v230 offset:39936
	ds_read_b128 v[212:215], v249 offset:4096
	ds_read_b128 v[232:235], v249 offset:5120
	global_load_lds_dwordx4 v198, s[98:99]
	s_mov_b32 m0, s48
	s_nop 0
	global_load_lds_dwordx4 v196, s[98:99]
	s_nop 0
	s_waitcnt vmcnt(9)
	s_waitcnt lgkmcnt(0)
	s_barrier
	s_setprio 1
	s_waitcnt lgkmcnt(0)
	v_mfma_f32_16x16x32_bf16 v[124:127], v[128:131], v[160:163], v[124:127]
	v_mfma_f32_16x16x32_bf16 v[120:123], v[136:139], v[160:163], v[120:123]
	v_mfma_f32_16x16x32_bf16 v[108:111], v[128:131], v[168:171], v[108:111]
	v_mfma_f32_16x16x32_bf16 v[104:107], v[136:139], v[168:171], v[104:107]
	v_mfma_f32_16x16x32_bf16 v[92:95], v[128:131], v[176:179], v[92:95]
	v_mfma_f32_16x16x32_bf16 v[88:91], v[136:139], v[176:179], v[88:91]
	v_mfma_f32_16x16x32_bf16 v[76:79], v[128:131], v[204:207], v[76:79]
	v_mfma_f32_16x16x32_bf16 v[72:75], v[136:139], v[204:207], v[72:75]
	v_mfma_f32_16x16x32_bf16 v[124:127], v[132:135], v[164:167], v[124:127]
	v_mfma_f32_16x16x32_bf16 v[120:123], v[140:143], v[164:167], v[120:123]
	v_mfma_f32_16x16x32_bf16 v[108:111], v[132:135], v[172:175], v[108:111]
	v_mfma_f32_16x16x32_bf16 v[104:107], v[140:143], v[172:175], v[104:107]
	v_mfma_f32_16x16x32_bf16 v[92:95], v[132:135], v[180:183], v[92:95]
	v_mfma_f32_16x16x32_bf16 v[88:91], v[140:143], v[180:183], v[88:91]
	v_mfma_f32_16x16x32_bf16 v[76:79], v[132:135], v[208:211], v[76:79]
	v_mfma_f32_16x16x32_bf16 v[72:75], v[140:143], v[208:211], v[72:75]
	s_setprio 0
	s_setprio 1
	v_mfma_f32_16x16x32_bf16 v[116:119], v[144:147], v[160:163], v[116:119]
	v_mfma_f32_16x16x32_bf16 v[112:115], v[152:155], v[160:163], v[112:115]
	v_mfma_f32_16x16x32_bf16 v[100:103], v[144:147], v[168:171], v[100:103]
	v_mfma_f32_16x16x32_bf16 v[96:99], v[152:155], v[168:171], v[96:99]
	v_mfma_f32_16x16x32_bf16 v[84:87], v[144:147], v[176:179], v[84:87]
	v_mfma_f32_16x16x32_bf16 v[80:83], v[152:155], v[176:179], v[80:83]
	v_mfma_f32_16x16x32_bf16 v[68:71], v[144:147], v[204:207], v[68:71]
	v_mfma_f32_16x16x32_bf16 v[64:67], v[152:155], v[204:207], v[64:67]
	v_mfma_f32_16x16x32_bf16 v[116:119], v[148:151], v[164:167], v[116:119]
	v_mfma_f32_16x16x32_bf16 v[112:115], v[156:159], v[164:167], v[112:115]
	v_mfma_f32_16x16x32_bf16 v[100:103], v[148:151], v[172:175], v[100:103]
	v_mfma_f32_16x16x32_bf16 v[96:99], v[156:159], v[172:175], v[96:99]
	v_mfma_f32_16x16x32_bf16 v[84:87], v[148:151], v[180:183], v[84:87]
	v_mfma_f32_16x16x32_bf16 v[80:83], v[156:159], v[180:183], v[80:83]
	v_mfma_f32_16x16x32_bf16 v[68:71], v[148:151], v[208:211], v[68:71]
	v_mfma_f32_16x16x32_bf16 v[64:67], v[156:159], v[208:211], v[64:67]
	v_mfma_f32_16x16x32_bf16 v[236:239], v[128:131], v[212:215], v[236:239]
	v_mfma_f32_16x16x32_bf16 v[240:243], v[136:139], v[212:215], v[240:243]
	v_mfma_f32_16x16x32_bf16 v[244:247], v[144:147], v[212:215], v[244:247]
	v_mfma_f32_16x16x32_bf16 v[200:203], v[152:155], v[212:215], v[200:203]
	v_mfma_f32_16x16x32_bf16 v[236:239], v[132:135], v[232:235], v[236:239]
	v_mfma_f32_16x16x32_bf16 v[240:243], v[140:143], v[232:235], v[240:243]
	v_mfma_f32_16x16x32_bf16 v[244:247], v[148:151], v[232:235], v[244:247]
	v_mfma_f32_16x16x32_bf16 v[200:203], v[156:159], v[232:235], v[200:203]
	s_setprio 0
	s_barrier
; #define PG8_STAGE(bufoff, gbase, voff) do { _Pragma("unroll") for (int _i = 0; _i < 2; ++_i) \
;         __builtin_amdgcn_global_load_lds((const unsigned*)((const char*)(gbase) + (voff)[_i]), (PG8_LAS unsigned*)(lds + (bufoff) + ldsw + _i * 8192), 16, 0, 0); } while (0)
; #define PG8_LDA(dst, b, h) do { _Pragma("unroll") for (int m = 0; m < 4; ++m) _Pragma("unroll") for (int k = 0; k < 2; ++k) dst[m][k] = *(const PG8_LAS bf16x8*)(lds + PG8_SA(b, h) + aoff + m * 2048 + k * 1024); } while (0)
; #define PG8_MMA(ai, bj, At, Bt) do { __builtin_amdgcn_s_setprio(1); _Pragma("unroll") for (int m = 0; m < 4; ++m) _Pragma("unroll") for (int n = 0; n < 2; ++n) _Pragma("unroll") for (int k = 0; k < 2; ++k) \
;         acc[ai][bj][m][n] = __builtin_amdgcn_mfma_f32_16x16x32_bf16(Bt[n][k], At[m][k], acc[ai][bj][m][n], 0, 0, 0); __builtin_amdgcn_s_setprio(0); } while (0)
; #define PG8_WAIT_V(n) asm volatile("s_waitcnt vmcnt(" #n ")" ::: "memory")
; #define PG8_WAIT_L(n) asm volatile("s_waitcnt lgkmcnt(" #n ")" ::: "memory")
; #define PG8_BAR __builtin_amdgcn_s_barrier()
; #define PG8_SCHED __builtin_amdgcn_sched_barrier(0)
; template <class Epi, class Sched, bool ALIGN_EPI = false, bool SP2 = false>
; __device__ __forceinline__ void gemm_phase(PG8_LAS unsigned char* lds, const Gemm g, const Sched& S, const Epi& E) {
;     ...
;             PG8_WAIT_V(8); PG8_WAIT_L(0); PG8_BAR; PG8_MMA(0, 0, At, B0); PG8_MMA(0, 1, At, B1); PG8_BAR; PG8_SCHED;
;             PG8_LDA(At, 1, 1); PG8_STAGE(PG8_SB(1, 0), b3, voffB); PG8_STAGE(PG8_SB(1, 1), b3 + hstep, voffB); PG8_STAGE(PG8_SA(1, 0), a3, voffA);
;             PG8_WAIT_V(8); PG8_WAIT_L(0); PG8_BAR; PG8_MMA(1, 0, At, B0); PG8_MMA(1, 1, At, B1); PG8_BAR; PG8_SCHED;
	s_add_i32 s25, s25, s44
	s_add_u32 s98, s40, 0x80
	s_addc_u32 s99, s41, 0
	s_mov_b32 m0, s25
	ds_read_b128 v[160:163], v230 offset:49152
	ds_read_b128 v[164:167], v230 offset:50176
	ds_read_b128 v[168:171], v230 offset:51200
	ds_read_b128 v[172:175], v230 offset:52224
	ds_read_b128 v[176:179], v230 offset:53248
	ds_read_b128 v[180:183], v230 offset:54272
	ds_read_b128 v[204:207], v230 offset:55296
	ds_read_b128 v[208:211], v230 offset:56320
	global_load_lds_dwordx4 v184, s[98:99]
	s_add_i32 m0, s25, 0x2000
	s_add_u32 s100, s40, 0x40080
	s_addc_u32 s101, s41, 0
	s_add_i32 s94, s94, s44
	global_load_lds_dwordx4 v194, s[98:99]
	s_mov_b32 m0, s94
	s_add_u32 s98, s42, 0x80
	s_addc_u32 s99, s43, 0
	global_load_lds_dwordx4 v184, s[100:101]
	s_add_i32 m0, s94, 0x2000
	s_nop 0
	global_load_lds_dwordx4 v194, s[100:101]
	s_mov_b32 m0, s51
	s_nop 0
	global_load_lds_dwordx4 v198, s[98:99]
	s_mov_b32 m0, s52
	s_nop 0
	global_load_lds_dwordx4 v196, s[98:99]
	s_and_b32 m0, s44, 0xc00
	s_add_i32 m0, m0, 0x21800
	s_nop 0
	global_load_lds_dwordx4 v248, s[98:99]
	s_waitcnt vmcnt(9)
	s_waitcnt lgkmcnt(0)
	s_barrier
	s_setprio 1
	s_waitcnt lgkmcnt(0)
	v_mfma_f32_16x16x32_bf16 v[60:63], v[128:131], v[160:163], v[60:63]
	v_mfma_f32_16x16x32_bf16 v[56:59], v[136:139], v[160:163], v[56:59]
	v_mfma_f32_16x16x32_bf16 v[44:47], v[128:131], v[168:171], v[44:47]
	v_mfma_f32_16x16x32_bf16 v[40:43], v[136:139], v[168:171], v[40:43]
	v_mfma_f32_16x16x32_bf16 v[28:31], v[128:131], v[176:179], v[28:31]
	v_mfma_f32_16x16x32_bf16 v[24:27], v[136:139], v[176:179], v[24:27]
	v_mfma_f32_16x16x32_bf16 v[12:15], v[128:131], v[204:207], v[12:15]
	v_mfma_f32_16x16x32_bf16 v[8:11], v[136:139], v[204:207], v[8:11]
	v_mfma_f32_16x16x32_bf16 v[60:63], v[132:135], v[164:167], v[60:63]
	v_mfma_f32_16x16x32_bf16 v[56:59], v[140:143], v[164:167], v[56:59]
	v_mfma_f32_16x16x32_bf16 v[44:47], v[132:135], v[172:175], v[44:47]
	v_mfma_f32_16x16x32_bf16 v[40:43], v[140:143], v[172:175], v[40:43]
	v_mfma_f32_16x16x32_bf16 v[28:31], v[132:135], v[180:183], v[28:31]
	v_mfma_f32_16x16x32_bf16 v[24:27], v[140:143], v[180:183], v[24:27]
	v_mfma_f32_16x16x32_bf16 v[12:15], v[132:135], v[208:211], v[12:15]
	v_mfma_f32_16x16x32_bf16 v[8:11], v[140:143], v[208:211], v[8:11]
	s_setprio 0
	s_setprio 1
	v_mfma_f32_16x16x32_bf16 v[52:55], v[144:147], v[160:163], v[52:55]
	v_mfma_f32_16x16x32_bf16 v[48:51], v[152:155], v[160:163], v[48:51]
	v_mfma_f32_16x16x32_bf16 v[36:39], v[144:147], v[168:171], v[36:39]
	v_mfma_f32_16x16x32_bf16 v[32:35], v[152:155], v[168:171], v[32:35]
	v_mfma_f32_16x16x32_bf16 v[20:23], v[144:147], v[176:179], v[20:23]
	v_mfma_f32_16x16x32_bf16 v[16:19], v[152:155], v[176:179], v[16:19]
	v_mfma_f32_16x16x32_bf16 v[4:7], v[144:147], v[204:207], v[4:7]
	v_mfma_f32_16x16x32_bf16 v[0:3], v[152:155], v[204:207], v[0:3]
	v_mfma_f32_16x16x32_bf16 v[52:55], v[148:151], v[164:167], v[52:55]
	v_mfma_f32_16x16x32_bf16 v[48:51], v[156:159], v[164:167], v[48:51]
	v_mfma_f32_16x16x32_bf16 v[36:39], v[148:151], v[172:175], v[36:39]
	v_mfma_f32_16x16x32_bf16 v[32:35], v[156:159], v[172:175], v[32:35]
	v_mfma_f32_16x16x32_bf16 v[20:23], v[148:151], v[180:183], v[20:23]
	v_mfma_f32_16x16x32_bf16 v[16:19], v[156:159], v[180:183], v[16:19]
	v_mfma_f32_16x16x32_bf16 v[4:7], v[148:151], v[208:211], v[4:7]
	v_mfma_f32_16x16x32_bf16 v[0:3], v[156:159], v[208:211], v[0:3]
	s_setprio 0
	s_barrier
	s_add_i32 s93, s93, 2
	s_add_u32 s0, s0, 0x100
	s_addc_u32 s1, s1, 0
	s_add_u32 s59, s59, 0x100
	s_addc_u32 s92, s92, 0
	s_cmp_gt_u32 s93, 13
	s_cbranch_scc0 .LBB0_218
	s_and_b64 vcc, exec, s[20:21]
	s_cbranch_vccz .LBB0_221
	s_barrier

; #define PG8_STAGE(bufoff, gbase, voff) do { _Pragma("unroll") for (int _i = 0; _i < 2; ++_i) \
;         __builtin_amdgcn_global_load_lds((const unsigned*)((const char*)(gbase) + (voff)[_i]), (PG8_LAS unsigned*)(lds + (bufoff) + ldsw + _i * 8192), 16, 0, 0); } while (0)
; #define PG8_LDA(dst, b, h) do { _Pragma("unroll") for (int m = 0; m < 4; ++m) _Pragma("unroll") for (int k = 0; k < 2; ++k) dst[m][k] = *(const PG8_LAS bf16x8*)(lds + PG8_SA(b, h) + aoff + m * 2048 + k * 1024); } while (0)
; #define PG8_LDB(dst, b, h) do { _Pragma("unroll") for (int n = 0; n < 2; ++n) _Pragma("unroll") for (int k = 0; k < 2; ++k) dst[n][k] = *(const PG8_LAS bf16x8*)(lds + PG8_SB(b, h) + boff + n * 2048 + k * 1024); } while (0)
; #define PG8_MMA(ai, bj, At, Bt) do { __builtin_amdgcn_s_setprio(1); _Pragma("unroll") for (int m = 0; m < 4; ++m) _Pragma("unroll") for (int n = 0; n < 2; ++n) _Pragma("unroll") for (int k = 0; k < 2; ++k) \
;         acc[ai][bj][m][n] = __builtin_amdgcn_mfma_f32_16x16x32_bf16(Bt[n][k], At[m][k], acc[ai][bj][m][n], 0, 0, 0); __builtin_amdgcn_s_setprio(0); } while (0)
; #define PG8_WAIT_V(n) asm volatile("s_waitcnt vmcnt(" #n ")" ::: "memory")
; #define PG8_WAIT_L(n) asm volatile("s_waitcnt lgkmcnt(" #n ")" ::: "memory")
; template <class Epi, class Sched, bool ALIGN_EPI = false, bool SP2 = false>
; __device__ __forceinline__ void gemm_phase(PG8_LAS unsigned char* lds, const Gemm g, const Sched& S, const Epi& E) {
;     ...
;             const bool last = (t == nt - 2);
;             const char* a1 = cA + (size_t)(t + 1) * kstep;
;             const char* a2 = last ? nA : cA + (size_t)(t + 2) * kstep; const char* b2 = last ? nB : cB + (size_t)(t + 2) * kstep;
;             const char* a3 = a2 + kstep; const char* b3 = b2 + kstep;
;             if (last && has_next) S.a_ready(nxt);
;             if constexpr (SP2) {
;             PG8_LDB(B0, 0, 0); PG8_LDB(B1, 0, 1); PG8_SCHED; PG8_LDA(At, 0, 0); PG8_STAGE(PG8_SA(1, 1), a1 + hstep, voffA);
;             PG8_WAIT_V(8); PG8_WAIT_L(0); PG8_BAR; PG8_MMA(0, 0, At, B0); PG8_MMA(0, 1, At, B1); PG8_BAR; PG8_SCHED;
;             PG8_LDA(At, 0, 1); PG8_STAGE(PG8_SB(0, 0), b2, voffB); PG8_STAGE(PG8_SB(0, 1), b2 + hstep, voffB); PG8_STAGE(PG8_SA(0, 0), a2, voffA);
;             PG8_WAIT_V(8); PG8_WAIT_L(0); PG8_BAR; PG8_MMA(1, 0, At, B0); PG8_MMA(1, 1, At, B1); PG8_BAR; PG8_SCHED;
.LBB0_461:
	s_add_u32 s0, s22, 0x100
	s_addc_u32 s1, s23, 0
	s_cmp_eq_u32 s50, 40
	s_cselect_b32 s27, s19, s1
	s_cselect_b32 s26, s18, s0
	s_cselect_b32 s25, s21, s5
	s_cselect_b32 s24, s20, s4
	s_add_i32 s6, 0, 0x10000
	s_add_i32 s51, 0, 0x14000
	v_add_u32_e32 v140, s6, v228
	v_add_u32_e32 v156, s51, v228
	ds_read_b128 v[128:131], v140
	ds_read_b128 v[132:135], v140 offset:1024
	ds_read_b128 v[136:139], v140 offset:2048
	ds_read_b128 v[140:143], v140 offset:3072
	ds_read_b128 v[144:147], v156
	ds_read_b128 v[148:151], v156 offset:1024
	ds_read_b128 v[152:155], v156 offset:2048
	ds_read_b128 v[156:159], v156 offset:3072
	s_add_u32 s98, s22, 0xb0080
	s_addc_u32 s99, s23, 0
	s_add_i32 m0, s30, 0xc000
	ds_read_b128 v[160:163], v230
	ds_read_b128 v[164:167], v230 offset:1024
	ds_read_b128 v[168:171], v230 offset:2048
	ds_read_b128 v[172:175], v230 offset:3072
	ds_read_b128 v[176:179], v230 offset:4096
	ds_read_b128 v[180:183], v230 offset:5120
	ds_read_b128 v[204:207], v230 offset:6144
	ds_read_b128 v[208:211], v230 offset:7168
	ds_read_b128 v[212:215], v249
	ds_read_b128 v[232:235], v249 offset:1024
	global_load_lds_dwordx4 v198, s[98:99]
	s_add_i32 m0, s30, 0xe000
	s_nop 0
	global_load_lds_dwordx4 v196, s[98:99]
	s_waitcnt vmcnt(9)
	s_waitcnt lgkmcnt(0)
	s_barrier
	s_setprio 1
	s_waitcnt lgkmcnt(0)
	v_mfma_f32_16x16x32_bf16 v[124:127], v[128:131], v[160:163], v[124:127]
	v_mfma_f32_16x16x32_bf16 v[120:123], v[136:139], v[160:163], v[120:123]
	v_mfma_f32_16x16x32_bf16 v[108:111], v[128:131], v[168:171], v[108:111]
	v_mfma_f32_16x16x32_bf16 v[104:107], v[136:139], v[168:171], v[104:107]
	v_mfma_f32_16x16x32_bf16 v[92:95], v[128:131], v[176:179], v[92:95]
	v_mfma_f32_16x16x32_bf16 v[88:91], v[136:139], v[176:179], v[88:91]
	v_mfma_f32_16x16x32_bf16 v[76:79], v[128:131], v[204:207], v[76:79]
	v_mfma_f32_16x16x32_bf16 v[72:75], v[136:139], v[204:207], v[72:75]
	v_mfma_f32_16x16x32_bf16 v[124:127], v[132:135], v[164:167], v[124:127]
	v_mfma_f32_16x16x32_bf16 v[120:123], v[140:143], v[164:167], v[120:123]
	v_mfma_f32_16x16x32_bf16 v[108:111], v[132:135], v[172:175], v[108:111]
	v_mfma_f32_16x16x32_bf16 v[104:107], v[140:143], v[172:175], v[104:107]
	v_mfma_f32_16x16x32_bf16 v[92:95], v[132:135], v[180:183], v[92:95]
	v_mfma_f32_16x16x32_bf16 v[88:91], v[140:143], v[180:183], v[88:91]
	v_mfma_f32_16x16x32_bf16 v[76:79], v[132:135], v[208:211], v[76:79]
	v_mfma_f32_16x16x32_bf16 v[72:75], v[140:143], v[208:211], v[72:75]
	s_setprio 0
	s_setprio 1
	v_mfma_f32_16x16x32_bf16 v[116:119], v[144:147], v[160:163], v[116:119]
	v_mfma_f32_16x16x32_bf16 v[112:115], v[152:155], v[160:163], v[112:115]
	v_mfma_f32_16x16x32_bf16 v[100:103], v[144:147], v[168:171], v[100:103]
	v_mfma_f32_16x16x32_bf16 v[96:99], v[152:155], v[168:171], v[96:99]
	v_mfma_f32_16x16x32_bf16 v[84:87], v[144:147], v[176:179], v[84:87]
	v_mfma_f32_16x16x32_bf16 v[80:83], v[152:155], v[176:179], v[80:83]
	v_mfma_f32_16x16x32_bf16 v[68:71], v[144:147], v[204:207], v[68:71]
	v_mfma_f32_16x16x32_bf16 v[64:67], v[152:155], v[204:207], v[64:67]
	v_mfma_f32_16x16x32_bf16 v[116:119], v[148:151], v[164:167], v[116:119]
	v_mfma_f32_16x16x32_bf16 v[112:115], v[156:159], v[164:167], v[112:115]
	v_mfma_f32_16x16x32_bf16 v[100:103], v[148:151], v[172:175], v[100:103]
	v_mfma_f32_16x16x32_bf16 v[96:99], v[156:159], v[172:175], v[96:99]
	v_mfma_f32_16x16x32_bf16 v[84:87], v[148:151], v[180:183], v[84:87]
	v_mfma_f32_16x16x32_bf16 v[80:83], v[156:159], v[180:183], v[80:83]
	v_mfma_f32_16x16x32_bf16 v[68:71], v[148:151], v[208:211], v[68:71]
	v_mfma_f32_16x16x32_bf16 v[64:67], v[156:159], v[208:211], v[64:67]
	v_mfma_f32_16x16x32_bf16 v[236:239], v[128:131], v[212:215], v[236:239]
	v_mfma_f32_16x16x32_bf16 v[240:243], v[136:139], v[212:215], v[240:243]
	v_mfma_f32_16x16x32_bf16 v[244:247], v[144:147], v[212:215], v[244:247]
	v_mfma_f32_16x16x32_bf16 v[200:203], v[152:155], v[212:215], v[200:203]
	v_mfma_f32_16x16x32_bf16 v[236:239], v[132:135], v[232:235], v[236:239]
	v_mfma_f32_16x16x32_bf16 v[240:243], v[140:143], v[232:235], v[240:243]
	v_mfma_f32_16x16x32_bf16 v[244:247], v[148:151], v[232:235], v[244:247]
	v_mfma_f32_16x16x32_bf16 v[200:203], v[156:159], v[232:235], v[200:203]
	s_setprio 0
	s_barrier
	s_add_i32 s6, s6, s29
	s_mov_b32 m0, s6
	ds_read_b128 v[160:163], v230 offset:16384
	ds_read_b128 v[164:167], v230 offset:17408
	ds_read_b128 v[168:171], v230 offset:18432
	ds_read_b128 v[172:175], v230 offset:19456
	ds_read_b128 v[176:179], v230 offset:20480
	ds_read_b128 v[180:183], v230 offset:21504
	ds_read_b128 v[204:207], v230 offset:22528
	ds_read_b128 v[208:211], v230 offset:23552
	global_load_lds_dwordx4 v184, s[24:25]
	s_add_i32 m0, s6, 0x2000
	s_add_u32 s22, s24, 0xb0000
	s_addc_u32 s23, s25, 0
	s_add_i32 s6, s51, s29
	global_load_lds_dwordx4 v194, s[24:25]
	s_mov_b32 m0, s6
	s_nop 0
	global_load_lds_dwordx4 v184, s[22:23]
	s_add_i32 m0, s6, 0x2000
	s_nop 0
	global_load_lds_dwordx4 v194, s[22:23]
	s_mov_b32 m0, s30
	s_nop 0
	global_load_lds_dwordx4 v198, s[26:27]
	s_mov_b32 m0, s31
	s_nop 0
	global_load_lds_dwordx4 v196, s[26:27]
	s_and_b32 m0, s30, 0xc00
	s_add_i32 m0, m0, 0x20800
	s_nop 0
	global_load_lds_dwordx4 v248, s[26:27]
	s_nop 0
	s_waitcnt vmcnt(9)
	s_waitcnt lgkmcnt(0)
	s_barrier
; #define PG8_STAGE(bufoff, gbase, voff) do { _Pragma("unroll") for (int _i = 0; _i < 2; ++_i) \
;         __builtin_amdgcn_global_load_lds((const unsigned*)((const char*)(gbase) + (voff)[_i]), (PG8_LAS unsigned*)(lds + (bufoff) + ldsw + _i * 8192), 16, 0, 0); } while (0)
; #define PG8_LDA(dst, b, h) do { _Pragma("unroll") for (int m = 0; m < 4; ++m) _Pragma("unroll") for (int k = 0; k < 2; ++k) dst[m][k] = *(const PG8_LAS bf16x8*)(lds + PG8_SA(b, h) + aoff + m * 2048 + k * 1024); } while (0)
; #define PG8_LDB(dst, b, h) do { _Pragma("unroll") for (int n = 0; n < 2; ++n) _Pragma("unroll") for (int k = 0; k < 2; ++k) dst[n][k] = *(const PG8_LAS bf16x8*)(lds + PG8_SB(b, h) + boff + n * 2048 + k * 1024); } while (0)
; #define PG8_MMA(ai, bj, At, Bt) do { __builtin_amdgcn_s_setprio(1); _Pragma("unroll") for (int m = 0; m < 4; ++m) _Pragma("unroll") for (int n = 0; n < 2; ++n) _Pragma("unroll") for (int k = 0; k < 2; ++k) \
;         acc[ai][bj][m][n] = __builtin_amdgcn_mfma_f32_16x16x32_bf16(Bt[n][k], At[m][k], acc[ai][bj][m][n], 0, 0, 0); __builtin_amdgcn_s_setprio(0); } while (0)
; #define PG8_WAIT_V(n) asm volatile("s_waitcnt vmcnt(" #n ")" ::: "memory")
; #define PG8_WAIT_L(n) asm volatile("s_waitcnt lgkmcnt(" #n ")" ::: "memory")
; #define PG8_BAR __builtin_amdgcn_s_barrier()
; #define PG8_SCHED __builtin_amdgcn_sched_barrier(0)
; template <class Epi, class Sched, bool ALIGN_EPI = false, bool SP2 = false>
; __device__ __forceinline__ void gemm_phase(PG8_LAS unsigned char* lds, const Gemm g, const Sched& S, const Epi& E) {
;     ...
;             PG8_WAIT_V(8); PG8_WAIT_L(0); PG8_BAR; PG8_MMA(1, 0, At, B0); PG8_MMA(1, 1, At, B1); PG8_BAR; PG8_SCHED;
;             PG8_LDB(B0, 1, 0); PG8_LDB(B1, 1, 1); PG8_SCHED; PG8_LDA(At, 1, 0); PG8_STAGE(PG8_SA(0, 1), a2 + hstep, voffA);
;             PG8_WAIT_V(8); PG8_WAIT_L(0); PG8_BAR; PG8_MMA(0, 0, At, B0); PG8_MMA(0, 1, At, B1); PG8_BAR; PG8_SCHED;
	s_setprio 1
	s_waitcnt lgkmcnt(0)
	v_mfma_f32_16x16x32_bf16 v[60:63], v[128:131], v[160:163], v[60:63]
	v_mfma_f32_16x16x32_bf16 v[56:59], v[136:139], v[160:163], v[56:59]
	v_mfma_f32_16x16x32_bf16 v[44:47], v[128:131], v[168:171], v[44:47]
	v_mfma_f32_16x16x32_bf16 v[40:43], v[136:139], v[168:171], v[40:43]
	v_mfma_f32_16x16x32_bf16 v[28:31], v[128:131], v[176:179], v[28:31]
	v_mfma_f32_16x16x32_bf16 v[24:27], v[136:139], v[176:179], v[24:27]
	v_mfma_f32_16x16x32_bf16 v[12:15], v[128:131], v[204:207], v[12:15]
	v_mfma_f32_16x16x32_bf16 v[8:11], v[136:139], v[204:207], v[8:11]
	v_mfma_f32_16x16x32_bf16 v[60:63], v[132:135], v[164:167], v[60:63]
	v_mfma_f32_16x16x32_bf16 v[56:59], v[140:143], v[164:167], v[56:59]
	v_mfma_f32_16x16x32_bf16 v[44:47], v[132:135], v[172:175], v[44:47]
	v_mfma_f32_16x16x32_bf16 v[40:43], v[140:143], v[172:175], v[40:43]
	v_mfma_f32_16x16x32_bf16 v[28:31], v[132:135], v[180:183], v[28:31]
	v_mfma_f32_16x16x32_bf16 v[24:27], v[140:143], v[180:183], v[24:27]
	v_mfma_f32_16x16x32_bf16 v[12:15], v[132:135], v[208:211], v[12:15]
	v_mfma_f32_16x16x32_bf16 v[8:11], v[140:143], v[208:211], v[8:11]
	s_setprio 0
	s_setprio 1
	v_mfma_f32_16x16x32_bf16 v[52:55], v[144:147], v[160:163], v[52:55]
	v_mfma_f32_16x16x32_bf16 v[48:51], v[152:155], v[160:163], v[48:51]
	v_mfma_f32_16x16x32_bf16 v[36:39], v[144:147], v[168:171], v[36:39]
	v_mfma_f32_16x16x32_bf16 v[32:35], v[152:155], v[168:171], v[32:35]
	v_mfma_f32_16x16x32_bf16 v[20:23], v[144:147], v[176:179], v[20:23]
	v_mfma_f32_16x16x32_bf16 v[16:19], v[152:155], v[176:179], v[16:19]
	v_mfma_f32_16x16x32_bf16 v[4:7], v[144:147], v[204:207], v[4:7]
	v_mfma_f32_16x16x32_bf16 v[0:3], v[152:155], v[204:207], v[0:3]
	v_mfma_f32_16x16x32_bf16 v[52:55], v[148:151], v[164:167], v[52:55]
	v_mfma_f32_16x16x32_bf16 v[48:51], v[156:159], v[164:167], v[48:51]
	v_mfma_f32_16x16x32_bf16 v[36:39], v[148:151], v[172:175], v[36:39]
	v_mfma_f32_16x16x32_bf16 v[32:35], v[156:159], v[172:175], v[32:35]
	v_mfma_f32_16x16x32_bf16 v[20:23], v[148:151], v[180:183], v[20:23]
	v_mfma_f32_16x16x32_bf16 v[16:19], v[156:159], v[180:183], v[16:19]
	v_mfma_f32_16x16x32_bf16 v[4:7], v[148:151], v[208:211], v[4:7]
	v_mfma_f32_16x16x32_bf16 v[0:3], v[156:159], v[208:211], v[0:3]
	s_setprio 0
	s_barrier
	s_add_i32 s6, 0, 0x18000
	s_add_i32 s51, 0, 0x1c000
	v_add_u32_e32 v140, s6, v228
	v_add_u32_e32 v156, s51, v228
	ds_read_b128 v[128:131], v140
	ds_read_b128 v[132:135], v140 offset:1024
	ds_read_b128 v[136:139], v140 offset:2048
	ds_read_b128 v[140:143], v140 offset:3072
	ds_read_b128 v[144:147], v156
	ds_read_b128 v[148:151], v156 offset:1024
	ds_read_b128 v[152:155], v156 offset:2048
	ds_read_b128 v[156:159], v156 offset:3072
	s_add_u32 s22, s26, 0xb0000
	s_addc_u32 s23, s27, 0
	s_mov_b32 m0, s34
	ds_read_b128 v[160:163], v230 offset:32768
	ds_read_b128 v[164:167], v230 offset:33792
	ds_read_b128 v[168:171], v230 offset:34816
	ds_read_b128 v[172:175], v230 offset:35840
	ds_read_b128 v[176:179], v230 offset:36864
	ds_read_b128 v[180:183], v230 offset:37888
	ds_read_b128 v[204:207], v230 offset:38912
	ds_read_b128 v[208:211], v230 offset:39936
	ds_read_b128 v[212:215], v249 offset:4096
	ds_read_b128 v[232:235], v249 offset:5120
	global_load_lds_dwordx4 v198, s[22:23]
	s_mov_b32 m0, s40
	s_nop 0
	global_load_lds_dwordx4 v196, s[22:23]
	s_nop 0
	s_waitcnt vmcnt(9)
	s_waitcnt lgkmcnt(0)
	s_barrier
	s_setprio 1
	s_waitcnt lgkmcnt(0)
	v_mfma_f32_16x16x32_bf16 v[124:127], v[128:131], v[160:163], v[124:127]
	v_mfma_f32_16x16x32_bf16 v[120:123], v[136:139], v[160:163], v[120:123]
	v_mfma_f32_16x16x32_bf16 v[108:111], v[128:131], v[168:171], v[108:111]
	v_mfma_f32_16x16x32_bf16 v[104:107], v[136:139], v[168:171], v[104:107]
	v_mfma_f32_16x16x32_bf16 v[92:95], v[128:131], v[176:179], v[92:95]
	v_mfma_f32_16x16x32_bf16 v[88:91], v[136:139], v[176:179], v[88:91]
	v_mfma_f32_16x16x32_bf16 v[76:79], v[128:131], v[204:207], v[76:79]
	v_mfma_f32_16x16x32_bf16 v[72:75], v[136:139], v[204:207], v[72:75]
	v_mfma_f32_16x16x32_bf16 v[124:127], v[132:135], v[164:167], v[124:127]
	v_mfma_f32_16x16x32_bf16 v[120:123], v[140:143], v[164:167], v[120:123]
	v_mfma_f32_16x16x32_bf16 v[108:111], v[132:135], v[172:175], v[108:111]
	v_mfma_f32_16x16x32_bf16 v[104:107], v[140:143], v[172:175], v[104:107]
	v_mfma_f32_16x16x32_bf16 v[92:95], v[132:135], v[180:183], v[92:95]
	v_mfma_f32_16x16x32_bf16 v[88:91], v[140:143], v[180:183], v[88:91]
	v_mfma_f32_16x16x32_bf16 v[76:79], v[132:135], v[208:211], v[76:79]
	v_mfma_f32_16x16x32_bf16 v[72:75], v[140:143], v[208:211], v[72:75]
	s_setprio 0
	s_setprio 1
	v_mfma_f32_16x16x32_bf16 v[116:119], v[144:147], v[160:163], v[116:119]
	v_mfma_f32_16x16x32_bf16 v[112:115], v[152:155], v[160:163], v[112:115]
	v_mfma_f32_16x16x32_bf16 v[100:103], v[144:147], v[168:171], v[100:103]
	v_mfma_f32_16x16x32_bf16 v[96:99], v[152:155], v[168:171], v[96:99]
	v_mfma_f32_16x16x32_bf16 v[84:87], v[144:147], v[176:179], v[84:87]
	v_mfma_f32_16x16x32_bf16 v[80:83], v[152:155], v[176:179], v[80:83]
	v_mfma_f32_16x16x32_bf16 v[68:71], v[144:147], v[204:207], v[68:71]
	v_mfma_f32_16x16x32_bf16 v[64:67], v[152:155], v[204:207], v[64:67]
	v_mfma_f32_16x16x32_bf16 v[116:119], v[148:151], v[164:167], v[116:119]
	v_mfma_f32_16x16x32_bf16 v[112:115], v[156:159], v[164:167], v[112:115]
	v_mfma_f32_16x16x32_bf16 v[100:103], v[148:151], v[172:175], v[100:103]
	v_mfma_f32_16x16x32_bf16 v[96:99], v[156:159], v[172:175], v[96:99]
	v_mfma_f32_16x16x32_bf16 v[84:87], v[148:151], v[180:183], v[84:87]
	v_mfma_f32_16x16x32_bf16 v[80:83], v[156:159], v[180:183], v[80:83]
	v_mfma_f32_16x16x32_bf16 v[68:71], v[148:151], v[208:211], v[68:71]
	v_mfma_f32_16x16x32_bf16 v[64:67], v[156:159], v[208:211], v[64:67]
	v_mfma_f32_16x16x32_bf16 v[236:239], v[128:131], v[212:215], v[236:239]
	v_mfma_f32_16x16x32_bf16 v[240:243], v[136:139], v[212:215], v[240:243]
	v_mfma_f32_16x16x32_bf16 v[244:247], v[144:147], v[212:215], v[244:247]
	v_mfma_f32_16x16x32_bf16 v[200:203], v[152:155], v[212:215], v[200:203]
	v_mfma_f32_16x16x32_bf16 v[236:239], v[132:135], v[232:235], v[236:239]
	v_mfma_f32_16x16x32_bf16 v[240:243], v[140:143], v[232:235], v[240:243]
	v_mfma_f32_16x16x32_bf16 v[244:247], v[148:151], v[232:235], v[244:247]
	v_mfma_f32_16x16x32_bf16 v[200:203], v[156:159], v[232:235], v[200:203]
	s_setprio 0
	s_barrier
; #define PG8_STAGE(bufoff, gbase, voff) do { _Pragma("unroll") for (int _i = 0; _i < 2; ++_i) \
;         __builtin_amdgcn_global_load_lds((const unsigned*)((const char*)(gbase) + (voff)[_i]), (PG8_LAS unsigned*)(lds + (bufoff) + ldsw + _i * 8192), 16, 0, 0); } while (0)
; #define PG8_LDA(dst, b, h) do { _Pragma("unroll") for (int m = 0; m < 4; ++m) _Pragma("unroll") for (int k = 0; k < 2; ++k) dst[m][k] = *(const PG8_LAS bf16x8*)(lds + PG8_SA(b, h) + aoff + m * 2048 + k * 1024); } while (0)
; #define PG8_MMA(ai, bj, At, Bt) do { __builtin_amdgcn_s_setprio(1); _Pragma("unroll") for (int m = 0; m < 4; ++m) _Pragma("unroll") for (int n = 0; n < 2; ++n) _Pragma("unroll") for (int k = 0; k < 2; ++k) \
;         acc[ai][bj][m][n] = __builtin_amdgcn_mfma_f32_16x16x32_bf16(Bt[n][k], At[m][k], acc[ai][bj][m][n], 0, 0, 0); __builtin_amdgcn_s_setprio(0); } while (0)
; #define PG8_WAIT_V(n) asm volatile("s_waitcnt vmcnt(" #n ")" ::: "memory")
; #define PG8_WAIT_L(n) asm volatile("s_waitcnt lgkmcnt(" #n ")" ::: "memory")
; #define PG8_BAR __builtin_amdgcn_s_barrier()
; #define PG8_SCHED __builtin_amdgcn_sched_barrier(0)
; template <class Epi, class Sched, bool ALIGN_EPI = false, bool SP2 = false>
; __device__ __forceinline__ void gemm_phase(PG8_LAS unsigned char* lds, const Gemm g, const Sched& S, const Epi& E) {
;     ...
;             PG8_WAIT_V(8); PG8_WAIT_L(0); PG8_BAR; PG8_MMA(0, 0, At, B0); PG8_MMA(0, 1, At, B1); PG8_BAR; PG8_SCHED;
;             PG8_LDA(At, 1, 1); PG8_STAGE(PG8_SB(1, 0), b3, voffB); PG8_STAGE(PG8_SB(1, 1), b3 + hstep, voffB); PG8_STAGE(PG8_SA(1, 0), a3, voffA);
;             PG8_WAIT_V(8); PG8_WAIT_L(0); PG8_BAR; PG8_MMA(1, 0, At, B0); PG8_MMA(1, 1, At, B1); PG8_BAR; PG8_SCHED;
	s_add_i32 s22, s6, s29
	s_add_u32 s98, s24, 0x80
	s_addc_u32 s99, s25, 0
	s_mov_b32 m0, s22
	ds_read_b128 v[160:163], v230 offset:49152
	ds_read_b128 v[164:167], v230 offset:50176
	ds_read_b128 v[168:171], v230 offset:51200
	ds_read_b128 v[172:175], v230 offset:52224
	ds_read_b128 v[176:179], v230 offset:53248
	ds_read_b128 v[180:183], v230 offset:54272
	ds_read_b128 v[204:207], v230 offset:55296
	ds_read_b128 v[208:211], v230 offset:56320
	global_load_lds_dwordx4 v184, s[98:99]
	s_add_i32 m0, s22, 0x2000
	s_add_u32 s100, s24, 0xb0080
	s_addc_u32 s101, s25, 0
	s_add_i32 s22, s51, s29
	global_load_lds_dwordx4 v194, s[98:99]
	s_mov_b32 m0, s22
	s_add_u32 s98, s26, 0x80
	s_addc_u32 s99, s27, 0
	global_load_lds_dwordx4 v184, s[100:101]
	s_add_i32 m0, s22, 0x2000
	s_nop 0
	global_load_lds_dwordx4 v194, s[100:101]
	s_mov_b32 m0, s41
	s_nop 0
	global_load_lds_dwordx4 v198, s[98:99]
	s_mov_b32 m0, s42
	s_nop 0
	global_load_lds_dwordx4 v196, s[98:99]
	s_and_b32 m0, s30, 0xc00
	s_add_i32 m0, m0, 0x21800
	s_nop 0
	global_load_lds_dwordx4 v248, s[98:99]
	s_waitcnt vmcnt(9)
	s_waitcnt lgkmcnt(0)
	s_barrier
	s_setprio 1
	s_waitcnt lgkmcnt(0)
	v_mfma_f32_16x16x32_bf16 v[60:63], v[128:131], v[160:163], v[60:63]
	v_mfma_f32_16x16x32_bf16 v[56:59], v[136:139], v[160:163], v[56:59]
	v_mfma_f32_16x16x32_bf16 v[44:47], v[128:131], v[168:171], v[44:47]
	v_mfma_f32_16x16x32_bf16 v[40:43], v[136:139], v[168:171], v[40:43]
	v_mfma_f32_16x16x32_bf16 v[28:31], v[128:131], v[176:179], v[28:31]
	v_mfma_f32_16x16x32_bf16 v[24:27], v[136:139], v[176:179], v[24:27]
	v_mfma_f32_16x16x32_bf16 v[12:15], v[128:131], v[204:207], v[12:15]
	v_mfma_f32_16x16x32_bf16 v[8:11], v[136:139], v[204:207], v[8:11]
	v_mfma_f32_16x16x32_bf16 v[60:63], v[132:135], v[164:167], v[60:63]
	v_mfma_f32_16x16x32_bf16 v[56:59], v[140:143], v[164:167], v[56:59]
	v_mfma_f32_16x16x32_bf16 v[44:47], v[132:135], v[172:175], v[44:47]
	v_mfma_f32_16x16x32_bf16 v[40:43], v[140:143], v[172:175], v[40:43]
	v_mfma_f32_16x16x32_bf16 v[28:31], v[132:135], v[180:183], v[28:31]
	v_mfma_f32_16x16x32_bf16 v[24:27], v[140:143], v[180:183], v[24:27]
	v_mfma_f32_16x16x32_bf16 v[12:15], v[132:135], v[208:211], v[12:15]
	v_mfma_f32_16x16x32_bf16 v[8:11], v[140:143], v[208:211], v[8:11]
	s_setprio 0
	s_setprio 1
	v_mfma_f32_16x16x32_bf16 v[52:55], v[144:147], v[160:163], v[52:55]
	v_mfma_f32_16x16x32_bf16 v[48:51], v[152:155], v[160:163], v[48:51]
	v_mfma_f32_16x16x32_bf16 v[36:39], v[144:147], v[168:171], v[36:39]
	v_mfma_f32_16x16x32_bf16 v[32:35], v[152:155], v[168:171], v[32:35]
	v_mfma_f32_16x16x32_bf16 v[20:23], v[144:147], v[176:179], v[20:23]
	v_mfma_f32_16x16x32_bf16 v[16:19], v[152:155], v[176:179], v[16:19]
	v_mfma_f32_16x16x32_bf16 v[4:7], v[144:147], v[204:207], v[4:7]
	v_mfma_f32_16x16x32_bf16 v[0:3], v[152:155], v[204:207], v[0:3]
	v_mfma_f32_16x16x32_bf16 v[52:55], v[148:151], v[164:167], v[52:55]
	v_mfma_f32_16x16x32_bf16 v[48:51], v[156:159], v[164:167], v[48:51]
	v_mfma_f32_16x16x32_bf16 v[36:39], v[148:151], v[172:175], v[36:39]
	v_mfma_f32_16x16x32_bf16 v[32:35], v[156:159], v[172:175], v[32:35]
	v_mfma_f32_16x16x32_bf16 v[20:23], v[148:151], v[180:183], v[20:23]
	v_mfma_f32_16x16x32_bf16 v[16:19], v[156:159], v[180:183], v[16:19]
	v_mfma_f32_16x16x32_bf16 v[4:7], v[148:151], v[208:211], v[4:7]
	v_mfma_f32_16x16x32_bf16 v[0:3], v[156:159], v[208:211], v[0:3]
	s_setprio 0
	s_barrier
	s_add_i32 s50, s50, 2
	s_add_u32 s4, s4, 0x100
	s_addc_u32 s5, s5, 0
	s_cmp_gt_u32 s50, 41
	s_mov_b64 s[22:23], s[0:1]
	s_cbranch_scc0 .LBB0_461
	s_and_b64 vcc, exec, s[16:17]
	s_cbranch_vccz .LBB0_464
	s_barrier
